# v20 + tighter polling at the grid seams (s_sleep 0 between polls)
# speedup vs baseline: 1.0018x; 1.0018x over previous
; __device__ __forceinline__ unsigned xb_ld(unsigned* p)              { return __hip_atomic_load(p, __ATOMIC_RELAXED, __HIP_MEMORY_SCOPE_AGENT); }
; __device__ __forceinline__ unsigned xb_add(unsigned* p, unsigned v) { return __hip_atomic_fetch_add(p, v, __ATOMIC_RELAXED, __HIP_MEMORY_SCOPE_AGENT); }
; #define XB_SPIN(cond, bar) do { unsigned _sp = 0; while (cond) { __builtin_amdgcn_s_sleep(1); \
;     if ((++_sp & 255u) == 0u) { if (xb_ld(&(bar)[XB_TMO])) break; if (_sp > XB_SPIN_CAP) { atomicAdd(&(bar)[XB_TMO], 1u); break; } } } } while (0)
; __device__ __forceinline__ void xcd_barrier(const XcdBarrier& b) {
;     ...
;             else XB_SPIN(xb_ld(&bar[XB_TOPGEN]) == tg, bar);
;             __builtin_amdgcn_fence(__ATOMIC_ACQUIRE, "agent");
;             xb_add(&bar[XB_XGEN(b.x)], 1u);
;             asm volatile("s_waitcnt vmcnt(0)" ::: "memory");
;         } else {
;             XB_SPIN(xb_ld(&bar[XB_XGEN(b.x)]) == gen, bar);
.LBB0_148:
	s_and_b32 s1, s0, 0xff
	s_mov_b64 s[22:23], -1
	s_cmp_lg_u32 s1, 0
	s_mov_b64 s[26:27], -1
	s_sleep 0
	s_cbranch_scc0 .LBB0_151
	s_and_b64 vcc, exec, s[26:27]
	s_cbranch_vccz .LBB0_147

; __device__ __forceinline__ unsigned xb_ld(unsigned* p)              { return __hip_atomic_load(p, __ATOMIC_RELAXED, __HIP_MEMORY_SCOPE_AGENT); }
; __device__ __forceinline__ unsigned xb_add(unsigned* p, unsigned v) { return __hip_atomic_fetch_add(p, v, __ATOMIC_RELAXED, __HIP_MEMORY_SCOPE_AGENT); }
; #define XB_SPIN(cond, bar) do { unsigned _sp = 0; while (cond) { __builtin_amdgcn_s_sleep(1); \
;     if ((++_sp & 255u) == 0u) { if (xb_ld(&(bar)[XB_TMO])) break; if (_sp > XB_SPIN_CAP) { atomicAdd(&(bar)[XB_TMO], 1u); break; } } } } while (0)
; __device__ __forceinline__ void xcd_barrier(const XcdBarrier& b) {
;     ...
;             else XB_SPIN(xb_ld(&bar[XB_TOPGEN]) == tg, bar);
;             __builtin_amdgcn_fence(__ATOMIC_ACQUIRE, "agent");
;             xb_add(&bar[XB_XGEN(b.x)], 1u);
;             asm volatile("s_waitcnt vmcnt(0)" ::: "memory");
;         } else {
;             XB_SPIN(xb_ld(&bar[XB_XGEN(b.x)]) == gen, bar);
.LBB0_165:
	s_and_b32 s1, s0, 0xff
	s_cmp_lg_u32 s1, 0
	s_mov_b64 s[24:25], -1
	s_sleep 0
	s_cbranch_scc0 .LBB0_168
	s_mov_b64 s[26:27], -1
	s_and_b64 vcc, exec, s[24:25]
	s_cbranch_vccz .LBB0_164

; __device__ __forceinline__ unsigned xb_ld(unsigned* p)              { return __hip_atomic_load(p, __ATOMIC_RELAXED, __HIP_MEMORY_SCOPE_AGENT); }
; __device__ __forceinline__ unsigned xb_add(unsigned* p, unsigned v) { return __hip_atomic_fetch_add(p, v, __ATOMIC_RELAXED, __HIP_MEMORY_SCOPE_AGENT); }
; #define XB_SPIN(cond, bar) do { unsigned _sp = 0; while (cond) { __builtin_amdgcn_s_sleep(1); \
;     if ((++_sp & 255u) == 0u) { if (xb_ld(&(bar)[XB_TMO])) break; if (_sp > XB_SPIN_CAP) { atomicAdd(&(bar)[XB_TMO], 1u); break; } } } } while (0)
; __device__ __forceinline__ void xcd_barrier(const XcdBarrier& b) {
;     ...
;             else XB_SPIN(xb_ld(&bar[XB_TOPGEN]) == tg, bar);
;             __builtin_amdgcn_fence(__ATOMIC_ACQUIRE, "agent");
;             xb_add(&bar[XB_XGEN(b.x)], 1u);
;             asm volatile("s_waitcnt vmcnt(0)" ::: "memory");
;         } else {
;             XB_SPIN(xb_ld(&bar[XB_XGEN(b.x)]) == gen, bar);
.LBB0_251:
	s_and_b32 s1, s0, 0xff
	s_mov_b64 s[34:35], -1
	s_cmp_lg_u32 s1, 0
	s_mov_b64 s[38:39], -1
	s_sleep 0
	s_cbranch_scc0 .LBB0_254
	s_and_b64 vcc, exec, s[38:39]
	s_cbranch_vccz .LBB0_250

; __device__ __forceinline__ unsigned xb_ld(unsigned* p)              { return __hip_atomic_load(p, __ATOMIC_RELAXED, __HIP_MEMORY_SCOPE_AGENT); }
; __device__ __forceinline__ unsigned xb_add(unsigned* p, unsigned v) { return __hip_atomic_fetch_add(p, v, __ATOMIC_RELAXED, __HIP_MEMORY_SCOPE_AGENT); }
; #define XB_SPIN(cond, bar) do { unsigned _sp = 0; while (cond) { __builtin_amdgcn_s_sleep(1); \
;     if ((++_sp & 255u) == 0u) { if (xb_ld(&(bar)[XB_TMO])) break; if (_sp > XB_SPIN_CAP) { atomicAdd(&(bar)[XB_TMO], 1u); break; } } } } while (0)
; __device__ __forceinline__ void xcd_barrier(const XcdBarrier& b) {
;     ...
;             else XB_SPIN(xb_ld(&bar[XB_TOPGEN]) == tg, bar);
;             __builtin_amdgcn_fence(__ATOMIC_ACQUIRE, "agent");
;             xb_add(&bar[XB_XGEN(b.x)], 1u);
;             asm volatile("s_waitcnt vmcnt(0)" ::: "memory");
;         } else {
;             XB_SPIN(xb_ld(&bar[XB_XGEN(b.x)]) == gen, bar);
.LBB0_268:
	s_and_b32 s1, s0, 0xff
	s_cmp_lg_u32 s1, 0
	s_mov_b64 s[36:37], -1
	s_sleep 0
	s_cbranch_scc0 .LBB0_271
	s_mov_b64 s[38:39], -1
	s_and_b64 vcc, exec, s[36:37]
	s_cbranch_vccz .LBB0_267

; __device__ __forceinline__ unsigned xb_ld(unsigned* p)              { return __hip_atomic_load(p, __ATOMIC_RELAXED, __HIP_MEMORY_SCOPE_AGENT); }
; __device__ __forceinline__ unsigned xb_add(unsigned* p, unsigned v) { return __hip_atomic_fetch_add(p, v, __ATOMIC_RELAXED, __HIP_MEMORY_SCOPE_AGENT); }
; #define XB_SPIN(cond, bar) do { unsigned _sp = 0; while (cond) { __builtin_amdgcn_s_sleep(1); \
;     if ((++_sp & 255u) == 0u) { if (xb_ld(&(bar)[XB_TMO])) break; if (_sp > XB_SPIN_CAP) { atomicAdd(&(bar)[XB_TMO], 1u); break; } } } } while (0)
; __device__ __forceinline__ void xcd_barrier(const XcdBarrier& b) {
;     ...
;             else XB_SPIN(xb_ld(&bar[XB_TOPGEN]) == tg, bar);
;             __builtin_amdgcn_fence(__ATOMIC_ACQUIRE, "agent");
;             xb_add(&bar[XB_XGEN(b.x)], 1u);
;             asm volatile("s_waitcnt vmcnt(0)" ::: "memory");
;         } else {
;             XB_SPIN(xb_ld(&bar[XB_XGEN(b.x)]) == gen, bar);
.LBB0_442:
	s_and_b32 s1, s0, 0xff
	s_mov_b64 s[20:21], -1
	s_cmp_lg_u32 s1, 0
	s_mov_b64 s[24:25], -1
	s_sleep 0
	s_cbranch_scc0 .LBB0_445
	s_and_b64 vcc, exec, s[24:25]
	s_cbranch_vccz .LBB0_441

; __device__ __forceinline__ unsigned xb_ld(unsigned* p)              { return __hip_atomic_load(p, __ATOMIC_RELAXED, __HIP_MEMORY_SCOPE_AGENT); }
; __device__ __forceinline__ unsigned xb_add(unsigned* p, unsigned v) { return __hip_atomic_fetch_add(p, v, __ATOMIC_RELAXED, __HIP_MEMORY_SCOPE_AGENT); }
; #define XB_SPIN(cond, bar) do { unsigned _sp = 0; while (cond) { __builtin_amdgcn_s_sleep(1); \
;     if ((++_sp & 255u) == 0u) { if (xb_ld(&(bar)[XB_TMO])) break; if (_sp > XB_SPIN_CAP) { atomicAdd(&(bar)[XB_TMO], 1u); break; } } } } while (0)
; __device__ __forceinline__ void xcd_barrier(const XcdBarrier& b) {
;     ...
;             else XB_SPIN(xb_ld(&bar[XB_TOPGEN]) == tg, bar);
;             __builtin_amdgcn_fence(__ATOMIC_ACQUIRE, "agent");
;             xb_add(&bar[XB_XGEN(b.x)], 1u);
;             asm volatile("s_waitcnt vmcnt(0)" ::: "memory");
;         } else {
;             XB_SPIN(xb_ld(&bar[XB_XGEN(b.x)]) == gen, bar);
.LBB0_459:
	s_and_b32 s1, s0, 0xff
	s_cmp_lg_u32 s1, 0
	s_mov_b64 s[22:23], -1
	s_sleep 0
	s_cbranch_scc0 .LBB0_462
	s_mov_b64 s[24:25], -1
	s_and_b64 vcc, exec, s[22:23]
	s_cbranch_vccz .LBB0_458

; __device__ __forceinline__ unsigned xb_ld(unsigned* p)              { return __hip_atomic_load(p, __ATOMIC_RELAXED, __HIP_MEMORY_SCOPE_AGENT); }
; __device__ __forceinline__ unsigned xb_add(unsigned* p, unsigned v) { return __hip_atomic_fetch_add(p, v, __ATOMIC_RELAXED, __HIP_MEMORY_SCOPE_AGENT); }
; #define XB_SPIN(cond, bar) do { unsigned _sp = 0; while (cond) { __builtin_amdgcn_s_sleep(1); \
;     if ((++_sp & 255u) == 0u) { if (xb_ld(&(bar)[XB_TMO])) break; if (_sp > XB_SPIN_CAP) { atomicAdd(&(bar)[XB_TMO], 1u); break; } } } } while (0)
; __device__ __forceinline__ void xcd_barrier(const XcdBarrier& b) {
;     ...
;             else XB_SPIN(xb_ld(&bar[XB_TOPGEN]) == tg, bar);
;             __builtin_amdgcn_fence(__ATOMIC_ACQUIRE, "agent");
;             xb_add(&bar[XB_XGEN(b.x)], 1u);
;             asm volatile("s_waitcnt vmcnt(0)" ::: "memory");
;         } else {
;             XB_SPIN(xb_ld(&bar[XB_XGEN(b.x)]) == gen, bar);
.LBB0_537:
	s_and_b32 s24, s28, 0xff
	s_mov_b64 s[22:23], -1
	s_cmp_lg_u32 s24, 0
	s_mov_b64 s[26:27], -1
	s_sleep 0
	s_cbranch_scc0 .LBB0_540
	s_and_b64 vcc, exec, s[26:27]
	s_cbranch_vccz .LBB0_536

; __device__ __forceinline__ unsigned xb_ld(unsigned* p)              { return __hip_atomic_load(p, __ATOMIC_RELAXED, __HIP_MEMORY_SCOPE_AGENT); }
; __device__ __forceinline__ unsigned xb_add(unsigned* p, unsigned v) { return __hip_atomic_fetch_add(p, v, __ATOMIC_RELAXED, __HIP_MEMORY_SCOPE_AGENT); }
; #define XB_SPIN(cond, bar) do { unsigned _sp = 0; while (cond) { __builtin_amdgcn_s_sleep(1); \
;     if ((++_sp & 255u) == 0u) { if (xb_ld(&(bar)[XB_TMO])) break; if (_sp > XB_SPIN_CAP) { atomicAdd(&(bar)[XB_TMO], 1u); break; } } } } while (0)
; __device__ __forceinline__ void xcd_barrier(const XcdBarrier& b) {
;     ...
;             else XB_SPIN(xb_ld(&bar[XB_TOPGEN]) == tg, bar);
;             __builtin_amdgcn_fence(__ATOMIC_ACQUIRE, "agent");
;             xb_add(&bar[XB_XGEN(b.x)], 1u);
;             asm volatile("s_waitcnt vmcnt(0)" ::: "memory");
;         } else {
;             XB_SPIN(xb_ld(&bar[XB_XGEN(b.x)]) == gen, bar);
.LBB0_554:
	s_and_b32 s22, s28, 0xff
	s_cmp_lg_u32 s22, 0
	s_mov_b64 s[24:25], -1
	s_sleep 0
	s_cbranch_scc0 .LBB0_557
	s_mov_b64 s[26:27], -1
	s_and_b64 vcc, exec, s[24:25]
	s_cbranch_vccz .LBB0_553
